# hand-written per-wave S5 output tasks (both directions through one wave-private LDS tile, no workgroup barriers) replace s5_out queue item bodies
# speedup vs baseline: 1.2510x; 1.0244x over previous
.LBB0_568:
	s_or_b64 exec, exec, s[38:39]
	s_waitcnt lgkmcnt(0)
	s_barrier
	ds_read_b32 v0, v208
	s_waitcnt lgkmcnt(0)
	v_readfirstlane_b32 s35, v0
	s_nop 0
	s_cmpk_lt_u32 s35, 0x300
	s_cbranch_scc1 .Ls5o_rm0
	s_add_u32 s35, s35, 0x180
.Ls5o_rm0:
	s_cmp_gt_i32 s35, s13
	s_cbranch_scc1 .LBB0_636
	s_lshl_b32 s4, s36, 2
	s_add_i32 s19, s62, 0xfffffc00
	s_lshl_b32 s5, s36, 1
	s_add_i32 s6, s36, 0xfffffe0
	v_writelane_b32 v234, s6, 0
	s_branch .LBB0_572

.Ls5o_rm1:
	s_cmp_gt_i32 s35, s13
	s_cbranch_scc1 .LBB0_636

.LBB0_575:
	s_andn2_b64 vcc, exec, s[38:39]
	s_cbranch_vccnz .LBB0_618
	v_and_b32_e32 v3, 63, v206
	v_lshrrev_b32_e32 v184, 6, v206
	v_and_b32_e32 v4, 15, v3
	v_readfirstlane_b32 s40, v184
	v_lshrrev_b32_e32 v5, 4, v3
	s_lshl_b32 s41, s63, 3
	s_add_u32 s41, s41, s40
	s_mul_i32 s42, s40, 16896
	v_mul_u32_u24_e32 v6, 2112, v5
	v_lshl_add_u32 v6, v4, 2, v6
	v_add_u32_e32 v6, s42, v6
	v_lshl_add_u32 v7, v3, 3, 0
	v_add_u32_e32 v7, s42, v7
	v_and_b32_e32 v8, 1, v5
	v_lshlrev_b32_e32 v8, 4, v8
	v_lshl_add_u32 v8, v4, 5, v8
	v_lshlrev_b32_e32 v9, 5, v3
	v_lshlrev_b32_e32 v10, 3, v3
	v_mul_u32_u24_e32 v13, 528, v4
	v_lshl_add_u32 v13, v5, 5, v13
	v_add_u32_e32 v13, s42, v13
	v_lshlrev_b32_e32 v14, 8, v4
	v_lshl_add_u32 v14, v5, 4, v14
	s_sub_u32 s100, s35, 0x180
	s_lshl_b32 s100, s100, 3
	s_add_u32 s100, s100, s40
	s_add_u32 s101, s100, 0x800
	s_sub_u32 s43, s100, 0x400
	s_cmpk_lt_u32 s100, 0x400
	s_cselect_b32 s100, s101, s43
	s_mov_b32 s43, 1
.Ls5o_task:
	s_lshr_b32 s98, s100, 4
	s_and_b32 s99, s100, 15
	s_cmpk_lt_u32 s98, 0x80
	s_cbranch_scc1 .Ls5o_ctx
	s_sub_u32 s100, s98, 0x80
	s_lshr_b32 s101, s100, 5
	s_and_b32 s38, s100, 31
	s_movk_i32 s39, 32
	s_lshl_b32 s54, s101, 5
	s_add_u32 s54, s54, 0x80
	s_add_u32 s47, s101, 16
	s_lshl_b32 s101, s101, 10
	s_lshl_b32 s100, s38, 1
	s_add_u32 s100, s100, s101
	s_add_u32 s100, s100, 0x1000
	s_mov_b32 s52, 0x91000
	s_movk_i32 s53, 0x2440
	s_mov_b32 s92, 0x8000
	s_movk_i32 s8, 0x200
	s_mov_b32 s55, 1
	s_branch .Ls5o_rows
.Ls5o_ctx:
	s_lshr_b32 s47, s98, 3
	s_and_b32 s38, s98, 7
	s_movk_i32 s39, 8
	s_lshl_b32 s54, s47, 3
	s_lshl_b32 s100, s98, 5
	s_movk_i32 s52, 0x2440
	s_mov_b32 s53, 0x24400
	s_movk_i32 s92, 0x200
	s_movk_i32 s8, 0x2000
	s_mov_b32 s55, 0
.Ls5o_rows:
	s_mov_b32 s46, s100
	s_mul_i32 s100, s100, 0x2440
	s_lshl_b32 s101, s99, 6
	s_add_u32 s100, s100, s101
	s_add_u32 s100, s100, 0x3a26040
	s_add_u32 s44, s96, s100
	s_addc_u32 s45, s97, 0
	s_lshl_b32 s100, s36, 4
	s_add_u32 s100, s100, s99
	s_lshl_b32 s101, s100, 12
	v_readlane_b32 s48, v237, 45
	v_readlane_b32 s49, v237, 46
	v_readlane_b32 s50, v237, 47
	v_readlane_b32 s51, v237, 48
	s_add_u32 s48, s48, s101
	s_addc_u32 s49, s49, 0
	s_add_u32 s50, s50, s101
	s_addc_u32 s51, s51, 0
	global_load_dwordx4 v[132:135], v14, s[48:49]
	global_load_dwordx4 v[148:151], v14, s[50:51]
	global_load_dwordx4 v[136:139], v14, s[48:49] offset:64
	global_load_dwordx4 v[152:155], v14, s[50:51] offset:64
	global_load_dwordx4 v[140:143], v14, s[48:49] offset:128
	global_load_dwordx4 v[156:159], v14, s[50:51] offset:128
	global_load_dwordx4 v[144:147], v14, s[48:49] offset:192
	global_load_dwordx4 v[160:163], v14, s[50:51] offset:192
	v_readlane_b32 s48, v237, 49
	v_readlane_b32 s49, v237, 50
	s_lshl_b32 s101, s100, 6
	s_add_u32 s48, s48, s101
	s_addc_u32 s49, s49, 0
	v_lshlrev_b32_e32 v184, 2, v4
	s_nop 0
	global_load_dword v164, v184, s[48:49]
	v_mul_lo_u32 v11, v4, s52
	v_lshl_add_u32 v11, v5, 5, v11
	v_add_u32_e32 v12, s53, v11
	v_mov_b32_e32 v20, 0
	v_mov_b32_e32 v21, 0
	v_mov_b32_e32 v22, 0
	v_mov_b32_e32 v23, 0
	v_mov_b32_e32 v24, 0
	v_mov_b32_e32 v25, 0
	v_mov_b32_e32 v26, 0
	v_mov_b32_e32 v27, 0
	v_mov_b32_e32 v28, 0
	v_mov_b32_e32 v29, 0
	v_mov_b32_e32 v30, 0
	v_mov_b32_e32 v31, 0
	v_mov_b32_e32 v32, 0
	v_mov_b32_e32 v33, 0
	v_mov_b32_e32 v34, 0
	v_mov_b32_e32 v35, 0
	s_mov_b64 s[56:57], exec
	s_mov_b32 exec_lo, -1
	s_mov_b32 exec_hi, 0
	global_load_dwordx4 v[20:23], v11, s[44:45]
	global_load_dwordx4 v[24:27], v11, s[44:45] offset:16
	global_load_dwordx4 v[28:31], v12, s[44:45]
	global_load_dwordx4 v[32:35], v12, s[44:45] offset:16
	s_mov_b64 exec, s[56:57]
	s_lshl_b32 s101, s52, 2
	v_mul_lo_u32 v17, v5, s101
	v_lshl_add_u32 v17, v4, 2, v17
	v_mov_b32_e32 v184, v17
	global_load_dword v165, v184, s[44:45]
	v_add_u32_e32 v184, s52, v184
	global_load_dword v166, v184, s[44:45]
	v_add_u32_e32 v184, s52, v184
	global_load_dword v167, v184, s[44:45]
	v_add_u32_e32 v184, s52, v184
	global_load_dword v168, v184, s[44:45]
	v_add_u32_e32 v184, s53, v17
	global_load_dword v169, v184, s[44:45]
	v_add_u32_e32 v184, s52, v184
	global_load_dword v170, v184, s[44:45]
	v_add_u32_e32 v184, s52, v184
	global_load_dword v171, v184, s[44:45]
	v_add_u32_e32 v184, s52, v184
	global_load_dword v172, v184, s[44:45]
	v_mov_b32_e32 v174, 0
	v_mov_b32_e32 v175, 0
	v_mov_b32_e32 v176, 0
	v_mov_b32_e32 v177, 0
	v_mov_b32_e32 v178, 0
	v_mov_b32_e32 v179, 0
	v_mov_b32_e32 v180, 0
	v_mov_b32_e32 v181, 0
	s_mov_b32 s56, 0
.Ls5o_dir:
	s_lshl_b32 s100, s36, 1
	s_add_u32 s100, s100, s56
	s_lshl_b32 s100, s100, 4
	s_add_u32 s100, s100, s99
	s_lshl_b32 s101, s100, 12
	s_add_u32 s101, s101, 0xd1c4000
	s_add_u32 s48, s96, s101
	s_addc_u32 s49, s97, 0
	global_load_dwordx4 v[44:47], v8, s[48:49]
	global_load_dwordx4 v[48:51], v8, s[48:49] offset:512
	global_load_dwordx4 v[52:55], v8, s[48:49] offset:1024
	global_load_dwordx4 v[56:59], v8, s[48:49] offset:1536
	global_load_dwordx4 v[60:63], v8, s[48:49] offset:2048
	global_load_dwordx4 v[64:67], v8, s[48:49] offset:2560
	global_load_dwordx4 v[68:71], v8, s[48:49] offset:3072
	global_load_dwordx4 v[72:75], v8, s[48:49] offset:3584
	s_lshl_b32 s101, s100, 11
	s_add_u32 s101, s101, 0xd1a4000
	s_add_u32 s48, s96, s101
	s_addc_u32 s49, s97, 0
	global_load_dwordx4 v[76:79], v9, s[48:49]
	global_load_dwordx2 v[80:81], v9, s[48:49] offset:16
	v_mov_b32_e32 v82, 0
	v_mov_b32_e32 v83, 0
	s_cmp_eq_u32 s55, 0
	s_cbranch_scc1 .Ls5o_nostate
	s_sub_u32 s100, s47, 16
	s_lshl_b32 s100, s100, 1
	s_add_u32 s100, s100, s36
	s_lshl_b32 s100, s100, 1
	s_add_u32 s100, s100, s56
	s_lshl_b32 s100, s100, 4
	s_add_u32 s100, s100, s99
	s_lshl_b32 s100, s100, 8
	v_lshl_add_u32 v184, v3, 2, s100
	s_nop 0
	global_load_dword v82, v184, s[74:75]
	global_load_dword v83, v184, s[76:77]
.Ls5o_nostate:
	s_sub_u32 s100, s39, 1
	s_sub_u32 s100, s100, s38
	s_add_u32 s101, s54, s39
	s_sub_u32 s101, s101, 1
	s_cmp_eq_u32 s56, 0
	s_cselect_b32 s57, s38, s100
	s_cselect_b32 s100, s54, s101
	s_lshl_b32 s100, s100, 4
	s_add_u32 s100, s100, s99
	s_lshl_b32 s100, s100, 1
	s_add_u32 s100, s100, s56
	s_lshl_b32 s100, s100, 9
	s_add_u32 s100, s100, 0xcba4000
	s_add_u32 s50, s96, s100
	s_addc_u32 s51, s97, 0
	s_cmp_eq_u32 s56, 0
	s_mov_b32 s58, 0xffffc000
	s_mov_b32 s59, -1
	s_cselect_b32 s58, 0x4000, s58
	s_cselect_b32 s59, 0, s59
	s_cmp_le_u32 s57, 0
	s_cbranch_scc1 .Ls5o_ei0
	global_load_dwordx2 v[84:85], v10, s[50:51]
	s_add_u32 s50, s50, s58
	s_addc_u32 s51, s51, s59
	s_cmp_le_u32 s57, 1
	s_cbranch_scc1 .Ls5o_ei0
	global_load_dwordx2 v[86:87], v10, s[50:51]
	s_add_u32 s50, s50, s58
	s_addc_u32 s51, s51, s59
	s_cmp_le_u32 s57, 2
	s_cbranch_scc1 .Ls5o_ei0
	global_load_dwordx2 v[88:89], v10, s[50:51]
	s_add_u32 s50, s50, s58
	s_addc_u32 s51, s51, s59
	s_cmp_le_u32 s57, 3
	s_cbranch_scc1 .Ls5o_ei0
	global_load_dwordx2 v[90:91], v10, s[50:51]
	s_add_u32 s50, s50, s58
	s_addc_u32 s51, s51, s59
	s_cmp_le_u32 s57, 4
	s_cbranch_scc1 .Ls5o_ei0
	global_load_dwordx2 v[92:93], v10, s[50:51]
	s_add_u32 s50, s50, s58
	s_addc_u32 s51, s51, s59
	s_cmp_le_u32 s57, 5
	s_cbranch_scc1 .Ls5o_ei0
	global_load_dwordx2 v[94:95], v10, s[50:51]
	s_add_u32 s50, s50, s58
	s_addc_u32 s51, s51, s59
	s_cmp_le_u32 s57, 6
	s_cbranch_scc1 .Ls5o_ei0
	global_load_dwordx2 v[96:97], v10, s[50:51]
	s_add_u32 s50, s50, s58
	s_addc_u32 s51, s51, s59
	s_cmp_le_u32 s57, 7
	s_cbranch_scc1 .Ls5o_ei0
	global_load_dwordx2 v[98:99], v10, s[50:51]
	s_add_u32 s50, s50, s58
	s_addc_u32 s51, s51, s59
	s_cmp_le_u32 s57, 8
	s_cbranch_scc1 .Ls5o_ei0
	global_load_dwordx2 v[100:101], v10, s[50:51]
	s_add_u32 s50, s50, s58
	s_addc_u32 s51, s51, s59
	s_cmp_le_u32 s57, 9
	s_cbranch_scc1 .Ls5o_ei0
	global_load_dwordx2 v[102:103], v10, s[50:51]
	s_add_u32 s50, s50, s58
	s_addc_u32 s51, s51, s59
	s_cmp_le_u32 s57, 10
	s_cbranch_scc1 .Ls5o_ei0
	global_load_dwordx2 v[104:105], v10, s[50:51]
	s_add_u32 s50, s50, s58
	s_addc_u32 s51, s51, s59
	s_cmp_le_u32 s57, 11
	s_cbranch_scc1 .Ls5o_ei0
	global_load_dwordx2 v[106:107], v10, s[50:51]
	s_add_u32 s50, s50, s58
	s_addc_u32 s51, s51, s59
	s_cmp_le_u32 s57, 12
	s_cbranch_scc1 .Ls5o_ei0
	global_load_dwordx2 v[108:109], v10, s[50:51]
	s_add_u32 s50, s50, s58
	s_addc_u32 s51, s51, s59
	s_cmp_le_u32 s57, 13
	s_cbranch_scc1 .Ls5o_ei0
	global_load_dwordx2 v[110:111], v10, s[50:51]
	s_add_u32 s50, s50, s58
	s_addc_u32 s51, s51, s59
	s_cmp_le_u32 s57, 14
	s_cbranch_scc1 .Ls5o_ei0
	global_load_dwordx2 v[112:113], v10, s[50:51]
	s_add_u32 s50, s50, s58
	s_addc_u32 s51, s51, s59
	s_cmp_le_u32 s57, 15
	s_cbranch_scc1 .Ls5o_ei0
	global_load_dwordx2 v[114:115], v10, s[50:51]
	s_add_u32 s50, s50, s58
	s_addc_u32 s51, s51, s59
.Ls5o_ei0:
	s_waitcnt vmcnt(0)
	s_cmp_lg_u32 s56, 0
	s_cbranch_scc1 .Ls5o_packed
	v_cvt_pk_bf16_f32 v36, v20, v21
	v_cvt_pk_bf16_f32 v37, v22, v23
	v_cvt_pk_bf16_f32 v38, v24, v25
	v_cvt_pk_bf16_f32 v39, v26, v27
	v_cvt_pk_bf16_f32 v40, v28, v29
	v_cvt_pk_bf16_f32 v41, v30, v31
	v_cvt_pk_bf16_f32 v42, v32, v33
	v_cvt_pk_bf16_f32 v43, v34, v35
	v_cvt_pk_bf16_f32 v116, v132, -v148
	v_cvt_pk_bf16_f32 v117, v133, -v149
	v_cvt_pk_bf16_f32 v118, v134, -v150
	v_cvt_pk_bf16_f32 v119, v135, -v151
	v_cvt_pk_bf16_f32 v120, v136, -v152
	v_cvt_pk_bf16_f32 v121, v137, -v153
	v_cvt_pk_bf16_f32 v122, v138, -v154
	v_cvt_pk_bf16_f32 v123, v139, -v155
	v_cvt_pk_bf16_f32 v124, v140, -v156
	v_cvt_pk_bf16_f32 v125, v141, -v157
	v_cvt_pk_bf16_f32 v126, v142, -v158
	v_cvt_pk_bf16_f32 v127, v143, -v159
	v_cvt_pk_bf16_f32 v128, v144, -v160
	v_cvt_pk_bf16_f32 v129, v145, -v161
	v_cvt_pk_bf16_f32 v130, v146, -v162
	v_cvt_pk_bf16_f32 v131, v147, -v163
.Ls5o_packed:
	s_nop 1
	v_mfma_f32_16x16x32_bf16 v[132:135], v[36:39], v[44:47], 0
	v_mfma_f32_16x16x32_bf16 v[136:139], v[40:43], v[44:47], 0
	v_mfma_f32_16x16x32_bf16 v[140:143], v[36:39], v[48:51], 0
	v_mfma_f32_16x16x32_bf16 v[144:147], v[40:43], v[48:51], 0
	v_mfma_f32_16x16x32_bf16 v[148:151], v[36:39], v[52:55], 0
	v_mfma_f32_16x16x32_bf16 v[152:155], v[40:43], v[52:55], 0
	v_mfma_f32_16x16x32_bf16 v[156:159], v[36:39], v[56:59], 0
	v_mfma_f32_16x16x32_bf16 v[160:163], v[40:43], v[56:59], 0
	s_nop 7
	ds_write_b32 v6, v132 offset:0
	ds_write_b32 v6, v133 offset:528
	ds_write_b32 v6, v134 offset:1056
	ds_write_b32 v6, v135 offset:1584
	ds_write_b32 v6, v136 offset:8448
	ds_write_b32 v6, v137 offset:8976
	ds_write_b32 v6, v138 offset:9504
	ds_write_b32 v6, v139 offset:10032
	ds_write_b32 v6, v140 offset:64
	ds_write_b32 v6, v141 offset:592
	ds_write_b32 v6, v142 offset:1120
	ds_write_b32 v6, v143 offset:1648
	ds_write_b32 v6, v144 offset:8512
	ds_write_b32 v6, v145 offset:9040
	ds_write_b32 v6, v146 offset:9568
	ds_write_b32 v6, v147 offset:10096
	ds_write_b32 v6, v148 offset:128
	ds_write_b32 v6, v149 offset:656
	ds_write_b32 v6, v150 offset:1184
	ds_write_b32 v6, v151 offset:1712
	ds_write_b32 v6, v152 offset:8576
	ds_write_b32 v6, v153 offset:9104
	ds_write_b32 v6, v154 offset:9632
	ds_write_b32 v6, v155 offset:10160
	ds_write_b32 v6, v156 offset:192
	ds_write_b32 v6, v157 offset:720
	ds_write_b32 v6, v158 offset:1248
	ds_write_b32 v6, v159 offset:1776
	ds_write_b32 v6, v160 offset:8640
	ds_write_b32 v6, v161 offset:9168
	ds_write_b32 v6, v162 offset:9696
	ds_write_b32 v6, v163 offset:10224
	s_nop 1
	v_mfma_f32_16x16x32_bf16 v[132:135], v[36:39], v[60:63], 0
	v_mfma_f32_16x16x32_bf16 v[136:139], v[40:43], v[60:63], 0
	v_mfma_f32_16x16x32_bf16 v[140:143], v[36:39], v[64:67], 0
	v_mfma_f32_16x16x32_bf16 v[144:147], v[40:43], v[64:67], 0
	v_mfma_f32_16x16x32_bf16 v[148:151], v[36:39], v[68:71], 0
	v_mfma_f32_16x16x32_bf16 v[152:155], v[40:43], v[68:71], 0
	v_mfma_f32_16x16x32_bf16 v[156:159], v[36:39], v[72:75], 0
	v_mfma_f32_16x16x32_bf16 v[160:163], v[40:43], v[72:75], 0
	s_nop 7
	ds_write_b32 v6, v132 offset:256
	ds_write_b32 v6, v133 offset:784
	ds_write_b32 v6, v134 offset:1312
	ds_write_b32 v6, v135 offset:1840
	ds_write_b32 v6, v136 offset:8704
	ds_write_b32 v6, v137 offset:9232
	ds_write_b32 v6, v138 offset:9760
	ds_write_b32 v6, v139 offset:10288
	ds_write_b32 v6, v140 offset:320
	ds_write_b32 v6, v141 offset:848
	ds_write_b32 v6, v142 offset:1376
	ds_write_b32 v6, v143 offset:1904
	ds_write_b32 v6, v144 offset:8768
	ds_write_b32 v6, v145 offset:9296
	ds_write_b32 v6, v146 offset:9824
	ds_write_b32 v6, v147 offset:10352
	ds_write_b32 v6, v148 offset:384
	ds_write_b32 v6, v149 offset:912
	ds_write_b32 v6, v150 offset:1440
	ds_write_b32 v6, v151 offset:1968
	ds_write_b32 v6, v152 offset:8832
	ds_write_b32 v6, v153 offset:9360
	ds_write_b32 v6, v154 offset:9888
	ds_write_b32 v6, v155 offset:10416
	ds_write_b32 v6, v156 offset:448
	ds_write_b32 v6, v157 offset:976
	ds_write_b32 v6, v158 offset:1504
	ds_write_b32 v6, v159 offset:2032
	ds_write_b32 v6, v160 offset:8896
	ds_write_b32 v6, v161 offset:9424
	ds_write_b32 v6, v162 offset:9952
	ds_write_b32 v6, v163 offset:10480
	v_mov_b32_e32 v182, v82
	v_mov_b32_e32 v183, v83
	s_cmp_le_u32 s57, 0
	s_cbranch_scc1 .Ls5o_ec1
	v_mul_f32_e32 v184, v81, v183
	v_mul_f32_e32 v185, v81, v182
	v_fma_f32 v0, v80, v182, -v184
	v_fma_f32 v1, v80, v183, v185
	v_add_f32_e32 v182, v0, v84
	v_add_f32_e32 v183, v1, v85
	s_cmp_le_u32 s57, 1
	s_cbranch_scc1 .Ls5o_ec1
	v_mul_f32_e32 v184, v81, v183
	v_mul_f32_e32 v185, v81, v182
	v_fma_f32 v0, v80, v182, -v184
	v_fma_f32 v1, v80, v183, v185
	v_add_f32_e32 v182, v0, v86
	v_add_f32_e32 v183, v1, v87
	s_cmp_le_u32 s57, 2
	s_cbranch_scc1 .Ls5o_ec1
	v_mul_f32_e32 v184, v81, v183
	v_mul_f32_e32 v185, v81, v182
	v_fma_f32 v0, v80, v182, -v184
	v_fma_f32 v1, v80, v183, v185
	v_add_f32_e32 v182, v0, v88
	v_add_f32_e32 v183, v1, v89
	s_cmp_le_u32 s57, 3
	s_cbranch_scc1 .Ls5o_ec1
	v_mul_f32_e32 v184, v81, v183
	v_mul_f32_e32 v185, v81, v182
	v_fma_f32 v0, v80, v182, -v184
	v_fma_f32 v1, v80, v183, v185
	v_add_f32_e32 v182, v0, v90
	v_add_f32_e32 v183, v1, v91
	s_cmp_le_u32 s57, 4
	s_cbranch_scc1 .Ls5o_ec1
	v_mul_f32_e32 v184, v81, v183
	v_mul_f32_e32 v185, v81, v182
	v_fma_f32 v0, v80, v182, -v184
	v_fma_f32 v1, v80, v183, v185
	v_add_f32_e32 v182, v0, v92
	v_add_f32_e32 v183, v1, v93
	s_cmp_le_u32 s57, 5
	s_cbranch_scc1 .Ls5o_ec1
	v_mul_f32_e32 v184, v81, v183
	v_mul_f32_e32 v185, v81, v182
	v_fma_f32 v0, v80, v182, -v184
	v_fma_f32 v1, v80, v183, v185
	v_add_f32_e32 v182, v0, v94
	v_add_f32_e32 v183, v1, v95
	s_cmp_le_u32 s57, 6
	s_cbranch_scc1 .Ls5o_ec1
	v_mul_f32_e32 v184, v81, v183
	v_mul_f32_e32 v185, v81, v182
	v_fma_f32 v0, v80, v182, -v184
	v_fma_f32 v1, v80, v183, v185
	v_add_f32_e32 v182, v0, v96
	v_add_f32_e32 v183, v1, v97
	s_cmp_le_u32 s57, 7
	s_cbranch_scc1 .Ls5o_ec1
	v_mul_f32_e32 v184, v81, v183
	v_mul_f32_e32 v185, v81, v182
	v_fma_f32 v0, v80, v182, -v184
	v_fma_f32 v1, v80, v183, v185
	v_add_f32_e32 v182, v0, v98
	v_add_f32_e32 v183, v1, v99
	s_cmp_le_u32 s57, 8
	s_cbranch_scc1 .Ls5o_ec1
	v_mul_f32_e32 v184, v81, v183
	v_mul_f32_e32 v185, v81, v182
	v_fma_f32 v0, v80, v182, -v184
	v_fma_f32 v1, v80, v183, v185
	v_add_f32_e32 v182, v0, v100
	v_add_f32_e32 v183, v1, v101
	s_cmp_le_u32 s57, 9
	s_cbranch_scc1 .Ls5o_ec1
	v_mul_f32_e32 v184, v81, v183
	v_mul_f32_e32 v185, v81, v182
	v_fma_f32 v0, v80, v182, -v184
	v_fma_f32 v1, v80, v183, v185
	v_add_f32_e32 v182, v0, v102
	v_add_f32_e32 v183, v1, v103
	s_cmp_le_u32 s57, 10
	s_cbranch_scc1 .Ls5o_ec1
	v_mul_f32_e32 v184, v81, v183
	v_mul_f32_e32 v185, v81, v182
	v_fma_f32 v0, v80, v182, -v184
	v_fma_f32 v1, v80, v183, v185
	v_add_f32_e32 v182, v0, v104
	v_add_f32_e32 v183, v1, v105
	s_cmp_le_u32 s57, 11
	s_cbranch_scc1 .Ls5o_ec1
	v_mul_f32_e32 v184, v81, v183
	v_mul_f32_e32 v185, v81, v182
	v_fma_f32 v0, v80, v182, -v184
	v_fma_f32 v1, v80, v183, v185
	v_add_f32_e32 v182, v0, v106
	v_add_f32_e32 v183, v1, v107
	s_cmp_le_u32 s57, 12
	s_cbranch_scc1 .Ls5o_ec1
	v_mul_f32_e32 v184, v81, v183
	v_mul_f32_e32 v185, v81, v182
	v_fma_f32 v0, v80, v182, -v184
	v_fma_f32 v1, v80, v183, v185
	v_add_f32_e32 v182, v0, v108
	v_add_f32_e32 v183, v1, v109
	s_cmp_le_u32 s57, 13
	s_cbranch_scc1 .Ls5o_ec1
	v_mul_f32_e32 v184, v81, v183
	v_mul_f32_e32 v185, v81, v182
	v_fma_f32 v0, v80, v182, -v184
	v_fma_f32 v1, v80, v183, v185
	v_add_f32_e32 v182, v0, v110
	v_add_f32_e32 v183, v1, v111
	s_cmp_le_u32 s57, 14
	s_cbranch_scc1 .Ls5o_ec1
	v_mul_f32_e32 v184, v81, v183
	v_mul_f32_e32 v185, v81, v182
	v_fma_f32 v0, v80, v182, -v184
	v_fma_f32 v1, v80, v183, v185
	v_add_f32_e32 v182, v0, v112
	v_add_f32_e32 v183, v1, v113
	s_cmp_le_u32 s57, 15
	s_cbranch_scc1 .Ls5o_ec1
	v_mul_f32_e32 v184, v81, v183
	v_mul_f32_e32 v185, v81, v182
	v_fma_f32 v0, v80, v182, -v184
	v_fma_f32 v1, v80, v183, v185
	v_add_f32_e32 v182, v0, v114
	v_add_f32_e32 v183, v1, v115
.Ls5o_ec1:
.Ls5o_pfloop:
	s_cmp_le_u32 s57, 16
	s_cbranch_scc1 .Ls5o_pfdone
	s_sub_u32 s57, s57, 16
	s_cmp_le_u32 s57, 0
	s_cbranch_scc1 .Ls5o_ei2
	global_load_dwordx2 v[84:85], v10, s[50:51]
	s_add_u32 s50, s50, s58
	s_addc_u32 s51, s51, s59
	s_cmp_le_u32 s57, 1
	s_cbranch_scc1 .Ls5o_ei2
	global_load_dwordx2 v[86:87], v10, s[50:51]
	s_add_u32 s50, s50, s58
	s_addc_u32 s51, s51, s59
	s_cmp_le_u32 s57, 2
	s_cbranch_scc1 .Ls5o_ei2
	global_load_dwordx2 v[88:89], v10, s[50:51]
	s_add_u32 s50, s50, s58
	s_addc_u32 s51, s51, s59
	s_cmp_le_u32 s57, 3
	s_cbranch_scc1 .Ls5o_ei2
	global_load_dwordx2 v[90:91], v10, s[50:51]
	s_add_u32 s50, s50, s58
	s_addc_u32 s51, s51, s59
	s_cmp_le_u32 s57, 4
	s_cbranch_scc1 .Ls5o_ei2
	global_load_dwordx2 v[92:93], v10, s[50:51]
	s_add_u32 s50, s50, s58
	s_addc_u32 s51, s51, s59
	s_cmp_le_u32 s57, 5
	s_cbranch_scc1 .Ls5o_ei2
	global_load_dwordx2 v[94:95], v10, s[50:51]
	s_add_u32 s50, s50, s58
	s_addc_u32 s51, s51, s59
	s_cmp_le_u32 s57, 6
	s_cbranch_scc1 .Ls5o_ei2
	global_load_dwordx2 v[96:97], v10, s[50:51]
	s_add_u32 s50, s50, s58
	s_addc_u32 s51, s51, s59
	s_cmp_le_u32 s57, 7
	s_cbranch_scc1 .Ls5o_ei2
	global_load_dwordx2 v[98:99], v10, s[50:51]
	s_add_u32 s50, s50, s58
	s_addc_u32 s51, s51, s59
	s_cmp_le_u32 s57, 8
	s_cbranch_scc1 .Ls5o_ei2
	global_load_dwordx2 v[100:101], v10, s[50:51]
	s_add_u32 s50, s50, s58
	s_addc_u32 s51, s51, s59
	s_cmp_le_u32 s57, 9
	s_cbranch_scc1 .Ls5o_ei2
	global_load_dwordx2 v[102:103], v10, s[50:51]
	s_add_u32 s50, s50, s58
	s_addc_u32 s51, s51, s59
	s_cmp_le_u32 s57, 10
	s_cbranch_scc1 .Ls5o_ei2
	global_load_dwordx2 v[104:105], v10, s[50:51]
	s_add_u32 s50, s50, s58
	s_addc_u32 s51, s51, s59
	s_cmp_le_u32 s57, 11
	s_cbranch_scc1 .Ls5o_ei2
	global_load_dwordx2 v[106:107], v10, s[50:51]
	s_add_u32 s50, s50, s58
	s_addc_u32 s51, s51, s59
	s_cmp_le_u32 s57, 12
	s_cbranch_scc1 .Ls5o_ei2
	global_load_dwordx2 v[108:109], v10, s[50:51]
	s_add_u32 s50, s50, s58
	s_addc_u32 s51, s51, s59
	s_cmp_le_u32 s57, 13
	s_cbranch_scc1 .Ls5o_ei2
	global_load_dwordx2 v[110:111], v10, s[50:51]
	s_add_u32 s50, s50, s58
	s_addc_u32 s51, s51, s59
	s_cmp_le_u32 s57, 14
	s_cbranch_scc1 .Ls5o_ei2
	global_load_dwordx2 v[112:113], v10, s[50:51]
	s_add_u32 s50, s50, s58
	s_addc_u32 s51, s51, s59
	s_cmp_le_u32 s57, 15
	s_cbranch_scc1 .Ls5o_ei2
	global_load_dwordx2 v[114:115], v10, s[50:51]
	s_add_u32 s50, s50, s58
	s_addc_u32 s51, s51, s59
.Ls5o_ei2:
	s_waitcnt vmcnt(0)
	s_cmp_le_u32 s57, 0
	s_cbranch_scc1 .Ls5o_ec3
	v_mul_f32_e32 v184, v81, v183
	v_mul_f32_e32 v185, v81, v182
	v_fma_f32 v0, v80, v182, -v184
	v_fma_f32 v1, v80, v183, v185
	v_add_f32_e32 v182, v0, v84
	v_add_f32_e32 v183, v1, v85
	s_cmp_le_u32 s57, 1
	s_cbranch_scc1 .Ls5o_ec3
	v_mul_f32_e32 v184, v81, v183
	v_mul_f32_e32 v185, v81, v182
	v_fma_f32 v0, v80, v182, -v184
	v_fma_f32 v1, v80, v183, v185
	v_add_f32_e32 v182, v0, v86
	v_add_f32_e32 v183, v1, v87
	s_cmp_le_u32 s57, 2
	s_cbranch_scc1 .Ls5o_ec3
	v_mul_f32_e32 v184, v81, v183
	v_mul_f32_e32 v185, v81, v182
	v_fma_f32 v0, v80, v182, -v184
	v_fma_f32 v1, v80, v183, v185
	v_add_f32_e32 v182, v0, v88
	v_add_f32_e32 v183, v1, v89
	s_cmp_le_u32 s57, 3
	s_cbranch_scc1 .Ls5o_ec3
	v_mul_f32_e32 v184, v81, v183
	v_mul_f32_e32 v185, v81, v182
	v_fma_f32 v0, v80, v182, -v184
	v_fma_f32 v1, v80, v183, v185
	v_add_f32_e32 v182, v0, v90
	v_add_f32_e32 v183, v1, v91
	s_cmp_le_u32 s57, 4
	s_cbranch_scc1 .Ls5o_ec3
	v_mul_f32_e32 v184, v81, v183
	v_mul_f32_e32 v185, v81, v182
	v_fma_f32 v0, v80, v182, -v184
	v_fma_f32 v1, v80, v183, v185
	v_add_f32_e32 v182, v0, v92
	v_add_f32_e32 v183, v1, v93
	s_cmp_le_u32 s57, 5
	s_cbranch_scc1 .Ls5o_ec3
	v_mul_f32_e32 v184, v81, v183
	v_mul_f32_e32 v185, v81, v182
	v_fma_f32 v0, v80, v182, -v184
	v_fma_f32 v1, v80, v183, v185
	v_add_f32_e32 v182, v0, v94
	v_add_f32_e32 v183, v1, v95
	s_cmp_le_u32 s57, 6
	s_cbranch_scc1 .Ls5o_ec3
	v_mul_f32_e32 v184, v81, v183
	v_mul_f32_e32 v185, v81, v182
	v_fma_f32 v0, v80, v182, -v184
	v_fma_f32 v1, v80, v183, v185
	v_add_f32_e32 v182, v0, v96
	v_add_f32_e32 v183, v1, v97
	s_cmp_le_u32 s57, 7
	s_cbranch_scc1 .Ls5o_ec3
	v_mul_f32_e32 v184, v81, v183
	v_mul_f32_e32 v185, v81, v182
	v_fma_f32 v0, v80, v182, -v184
	v_fma_f32 v1, v80, v183, v185
	v_add_f32_e32 v182, v0, v98
	v_add_f32_e32 v183, v1, v99
	s_cmp_le_u32 s57, 8
	s_cbranch_scc1 .Ls5o_ec3
	v_mul_f32_e32 v184, v81, v183
	v_mul_f32_e32 v185, v81, v182
	v_fma_f32 v0, v80, v182, -v184
	v_fma_f32 v1, v80, v183, v185
	v_add_f32_e32 v182, v0, v100
	v_add_f32_e32 v183, v1, v101
	s_cmp_le_u32 s57, 9
	s_cbranch_scc1 .Ls5o_ec3
	v_mul_f32_e32 v184, v81, v183
	v_mul_f32_e32 v185, v81, v182
	v_fma_f32 v0, v80, v182, -v184
	v_fma_f32 v1, v80, v183, v185
	v_add_f32_e32 v182, v0, v102
	v_add_f32_e32 v183, v1, v103
	s_cmp_le_u32 s57, 10
	s_cbranch_scc1 .Ls5o_ec3
	v_mul_f32_e32 v184, v81, v183
	v_mul_f32_e32 v185, v81, v182
	v_fma_f32 v0, v80, v182, -v184
	v_fma_f32 v1, v80, v183, v185
	v_add_f32_e32 v182, v0, v104
	v_add_f32_e32 v183, v1, v105
	s_cmp_le_u32 s57, 11
	s_cbranch_scc1 .Ls5o_ec3
	v_mul_f32_e32 v184, v81, v183
	v_mul_f32_e32 v185, v81, v182
	v_fma_f32 v0, v80, v182, -v184
	v_fma_f32 v1, v80, v183, v185
	v_add_f32_e32 v182, v0, v106
	v_add_f32_e32 v183, v1, v107
	s_cmp_le_u32 s57, 12
	s_cbranch_scc1 .Ls5o_ec3
	v_mul_f32_e32 v184, v81, v183
	v_mul_f32_e32 v185, v81, v182
	v_fma_f32 v0, v80, v182, -v184
	v_fma_f32 v1, v80, v183, v185
	v_add_f32_e32 v182, v0, v108
	v_add_f32_e32 v183, v1, v109
	s_cmp_le_u32 s57, 13
	s_cbranch_scc1 .Ls5o_ec3
	v_mul_f32_e32 v184, v81, v183
	v_mul_f32_e32 v185, v81, v182
	v_fma_f32 v0, v80, v182, -v184
	v_fma_f32 v1, v80, v183, v185
	v_add_f32_e32 v182, v0, v110
	v_add_f32_e32 v183, v1, v111
	s_cmp_le_u32 s57, 14
	s_cbranch_scc1 .Ls5o_ec3
	v_mul_f32_e32 v184, v81, v183
	v_mul_f32_e32 v185, v81, v182
	v_fma_f32 v0, v80, v182, -v184
	v_fma_f32 v1, v80, v183, v185
	v_add_f32_e32 v182, v0, v112
	v_add_f32_e32 v183, v1, v113
	s_cmp_le_u32 s57, 15
	s_cbranch_scc1 .Ls5o_ec3
	v_mul_f32_e32 v184, v81, v183
	v_mul_f32_e32 v185, v81, v182
	v_fma_f32 v0, v80, v182, -v184
	v_fma_f32 v1, v80, v183, v185
	v_add_f32_e32 v182, v0, v114
	v_add_f32_e32 v183, v1, v115
.Ls5o_ec3:
	s_branch .Ls5o_pfloop
.Ls5o_pfdone:
	s_cmp_eq_u32 s56, 0
	s_cselect_b32 s100, 0, 16368
	s_mov_b32 s101, 0xfffffdf0
	s_cselect_b32 s101, 528, s101
	v_add_u32_e32 v15, s100, v7
	v_mov_b32_e32 v16, v15
	s_waitcnt lgkmcnt(0)
	ds_read_b64 v[132:133], v15
	v_add_u32_e32 v15, s101, v15
	ds_read_b64 v[134:135], v15
	v_add_u32_e32 v15, s101, v15
	ds_read_b64 v[136:137], v15
	v_add_u32_e32 v15, s101, v15
	ds_read_b64 v[138:139], v15
	v_add_u32_e32 v15, s101, v15
	ds_read_b64 v[140:141], v15
	v_add_u32_e32 v15, s101, v15
	ds_read_b64 v[142:143], v15
	v_add_u32_e32 v15, s101, v15
	ds_read_b64 v[144:145], v15
	v_add_u32_e32 v15, s101, v15
	ds_read_b64 v[146:147], v15
	v_add_u32_e32 v15, s101, v15
	s_waitcnt lgkmcnt(7)
	v_mul_f32_e32 v184, v77, v183
	v_mul_f32_e32 v185, v77, v182
	v_fma_f32 v0, v76, v182, -v184
	v_fma_f32 v1, v76, v183, v185
	v_add_f32_e32 v182, v0, v132
	v_add_f32_e32 v183, v1, v133
	ds_write_b64 v16, v[182:183]
	v_add_u32_e32 v16, s101, v16
	ds_read_b64 v[132:133], v15
	v_add_u32_e32 v15, s101, v15
	s_waitcnt lgkmcnt(8)
	v_mul_f32_e32 v184, v77, v183
	v_mul_f32_e32 v185, v77, v182
	v_fma_f32 v0, v76, v182, -v184
	v_fma_f32 v1, v76, v183, v185
	v_add_f32_e32 v182, v0, v134
	v_add_f32_e32 v183, v1, v135
	ds_write_b64 v16, v[182:183]
	v_add_u32_e32 v16, s101, v16
	ds_read_b64 v[134:135], v15
	v_add_u32_e32 v15, s101, v15
	s_waitcnt lgkmcnt(9)
	v_mul_f32_e32 v184, v77, v183
	v_mul_f32_e32 v185, v77, v182
	v_fma_f32 v0, v76, v182, -v184
	v_fma_f32 v1, v76, v183, v185
	v_add_f32_e32 v182, v0, v136
	v_add_f32_e32 v183, v1, v137
	ds_write_b64 v16, v[182:183]
	v_add_u32_e32 v16, s101, v16
	ds_read_b64 v[136:137], v15
	v_add_u32_e32 v15, s101, v15
	s_waitcnt lgkmcnt(10)
	v_mul_f32_e32 v184, v77, v183
	v_mul_f32_e32 v185, v77, v182
	v_fma_f32 v0, v76, v182, -v184
	v_fma_f32 v1, v76, v183, v185
	v_add_f32_e32 v182, v0, v138
	v_add_f32_e32 v183, v1, v139
	ds_write_b64 v16, v[182:183]
	v_add_u32_e32 v16, s101, v16
	ds_read_b64 v[138:139], v15
	v_add_u32_e32 v15, s101, v15
	s_waitcnt lgkmcnt(11)
	v_mul_f32_e32 v184, v77, v183
	v_mul_f32_e32 v185, v77, v182
	v_fma_f32 v0, v76, v182, -v184
	v_fma_f32 v1, v76, v183, v185
	v_add_f32_e32 v182, v0, v140
	v_add_f32_e32 v183, v1, v141
	ds_write_b64 v16, v[182:183]
	v_add_u32_e32 v16, s101, v16
	ds_read_b64 v[140:141], v15
	v_add_u32_e32 v15, s101, v15
	s_waitcnt lgkmcnt(12)
	v_mul_f32_e32 v184, v77, v183
	v_mul_f32_e32 v185, v77, v182
	v_fma_f32 v0, v76, v182, -v184
	v_fma_f32 v1, v76, v183, v185
	v_add_f32_e32 v182, v0, v142
	v_add_f32_e32 v183, v1, v143
	ds_write_b64 v16, v[182:183]
	v_add_u32_e32 v16, s101, v16
	ds_read_b64 v[142:143], v15
	v_add_u32_e32 v15, s101, v15
	s_waitcnt lgkmcnt(13)
	v_mul_f32_e32 v184, v77, v183
	v_mul_f32_e32 v185, v77, v182
	v_fma_f32 v0, v76, v182, -v184
	v_fma_f32 v1, v76, v183, v185
	v_add_f32_e32 v182, v0, v144
	v_add_f32_e32 v183, v1, v145
	ds_write_b64 v16, v[182:183]
	v_add_u32_e32 v16, s101, v16
	ds_read_b64 v[144:145], v15
	v_add_u32_e32 v15, s101, v15
	s_waitcnt lgkmcnt(14)
	v_mul_f32_e32 v184, v77, v183
	v_mul_f32_e32 v185, v77, v182
	v_fma_f32 v0, v76, v182, -v184
	v_fma_f32 v1, v76, v183, v185
	v_add_f32_e32 v182, v0, v146
	v_add_f32_e32 v183, v1, v147
	ds_write_b64 v16, v[182:183]
	v_add_u32_e32 v16, s101, v16
	ds_read_b64 v[146:147], v15
	v_add_u32_e32 v15, s101, v15
	s_waitcnt lgkmcnt(14)
	v_mul_f32_e32 v184, v77, v183
	v_mul_f32_e32 v185, v77, v182
	v_fma_f32 v0, v76, v182, -v184
	v_fma_f32 v1, v76, v183, v185
	v_add_f32_e32 v182, v0, v132
	v_add_f32_e32 v183, v1, v133
	ds_write_b64 v16, v[182:183]
	v_add_u32_e32 v16, s101, v16
	ds_read_b64 v[132:133], v15
	v_add_u32_e32 v15, s101, v15
	s_waitcnt lgkmcnt(14)
	v_mul_f32_e32 v184, v77, v183
	v_mul_f32_e32 v185, v77, v182
	v_fma_f32 v0, v76, v182, -v184
	v_fma_f32 v1, v76, v183, v185
	v_add_f32_e32 v182, v0, v134
	v_add_f32_e32 v183, v1, v135
	ds_write_b64 v16, v[182:183]
	v_add_u32_e32 v16, s101, v16
	ds_read_b64 v[134:135], v15
	v_add_u32_e32 v15, s101, v15
	s_waitcnt lgkmcnt(14)
	v_mul_f32_e32 v184, v77, v183
	v_mul_f32_e32 v185, v77, v182
	v_fma_f32 v0, v76, v182, -v184
	v_fma_f32 v1, v76, v183, v185
	v_add_f32_e32 v182, v0, v136
	v_add_f32_e32 v183, v1, v137
	ds_write_b64 v16, v[182:183]
	v_add_u32_e32 v16, s101, v16
	ds_read_b64 v[136:137], v15
	v_add_u32_e32 v15, s101, v15
	s_waitcnt lgkmcnt(14)
	v_mul_f32_e32 v184, v77, v183
	v_mul_f32_e32 v185, v77, v182
	v_fma_f32 v0, v76, v182, -v184
	v_fma_f32 v1, v76, v183, v185
	v_add_f32_e32 v182, v0, v138
	v_add_f32_e32 v183, v1, v139
	ds_write_b64 v16, v[182:183]
	v_add_u32_e32 v16, s101, v16
	ds_read_b64 v[138:139], v15
	v_add_u32_e32 v15, s101, v15
	s_waitcnt lgkmcnt(14)
	v_mul_f32_e32 v184, v77, v183
	v_mul_f32_e32 v185, v77, v182
	v_fma_f32 v0, v76, v182, -v184
	v_fma_f32 v1, v76, v183, v185
	v_add_f32_e32 v182, v0, v140
	v_add_f32_e32 v183, v1, v141
	ds_write_b64 v16, v[182:183]
	v_add_u32_e32 v16, s101, v16
	ds_read_b64 v[140:141], v15
	v_add_u32_e32 v15, s101, v15
	s_waitcnt lgkmcnt(14)
	v_mul_f32_e32 v184, v77, v183
	v_mul_f32_e32 v185, v77, v182
	v_fma_f32 v0, v76, v182, -v184
	v_fma_f32 v1, v76, v183, v185
	v_add_f32_e32 v182, v0, v142
	v_add_f32_e32 v183, v1, v143
	ds_write_b64 v16, v[182:183]
	v_add_u32_e32 v16, s101, v16
	ds_read_b64 v[142:143], v15
	v_add_u32_e32 v15, s101, v15
	s_waitcnt lgkmcnt(14)
	v_mul_f32_e32 v184, v77, v183
	v_mul_f32_e32 v185, v77, v182
	v_fma_f32 v0, v76, v182, -v184
	v_fma_f32 v1, v76, v183, v185
	v_add_f32_e32 v182, v0, v144
	v_add_f32_e32 v183, v1, v145
	ds_write_b64 v16, v[182:183]
	v_add_u32_e32 v16, s101, v16
	ds_read_b64 v[144:145], v15
	v_add_u32_e32 v15, s101, v15
	s_waitcnt lgkmcnt(14)
	v_mul_f32_e32 v184, v77, v183
	v_mul_f32_e32 v185, v77, v182
	v_fma_f32 v0, v76, v182, -v184
	v_fma_f32 v1, v76, v183, v185
	v_add_f32_e32 v182, v0, v146
	v_add_f32_e32 v183, v1, v147
	ds_write_b64 v16, v[182:183]
	v_add_u32_e32 v16, s101, v16
	ds_read_b64 v[146:147], v15
	v_add_u32_e32 v15, s101, v15
	s_waitcnt lgkmcnt(14)
	v_mul_f32_e32 v184, v77, v183
	v_mul_f32_e32 v185, v77, v182
	v_fma_f32 v0, v76, v182, -v184
	v_fma_f32 v1, v76, v183, v185
	v_add_f32_e32 v182, v0, v132
	v_add_f32_e32 v183, v1, v133
	ds_write_b64 v16, v[182:183]
	v_add_u32_e32 v16, s101, v16
	ds_read_b64 v[132:133], v15
	v_add_u32_e32 v15, s101, v15
	s_waitcnt lgkmcnt(14)
	v_mul_f32_e32 v184, v77, v183
	v_mul_f32_e32 v185, v77, v182
	v_fma_f32 v0, v76, v182, -v184
	v_fma_f32 v1, v76, v183, v185
	v_add_f32_e32 v182, v0, v134
	v_add_f32_e32 v183, v1, v135
	ds_write_b64 v16, v[182:183]
	v_add_u32_e32 v16, s101, v16
	ds_read_b64 v[134:135], v15
	v_add_u32_e32 v15, s101, v15
	s_waitcnt lgkmcnt(14)
	v_mul_f32_e32 v184, v77, v183
	v_mul_f32_e32 v185, v77, v182
	v_fma_f32 v0, v76, v182, -v184
	v_fma_f32 v1, v76, v183, v185
	v_add_f32_e32 v182, v0, v136
	v_add_f32_e32 v183, v1, v137
	ds_write_b64 v16, v[182:183]
	v_add_u32_e32 v16, s101, v16
	ds_read_b64 v[136:137], v15
	v_add_u32_e32 v15, s101, v15
	s_waitcnt lgkmcnt(14)
	v_mul_f32_e32 v184, v77, v183
	v_mul_f32_e32 v185, v77, v182
	v_fma_f32 v0, v76, v182, -v184
	v_fma_f32 v1, v76, v183, v185
	v_add_f32_e32 v182, v0, v138
	v_add_f32_e32 v183, v1, v139
	ds_write_b64 v16, v[182:183]
	v_add_u32_e32 v16, s101, v16
	ds_read_b64 v[138:139], v15
	v_add_u32_e32 v15, s101, v15
	s_waitcnt lgkmcnt(14)
	v_mul_f32_e32 v184, v77, v183
	v_mul_f32_e32 v185, v77, v182
	v_fma_f32 v0, v76, v182, -v184
	v_fma_f32 v1, v76, v183, v185
	v_add_f32_e32 v182, v0, v140
	v_add_f32_e32 v183, v1, v141
	ds_write_b64 v16, v[182:183]
	v_add_u32_e32 v16, s101, v16
	ds_read_b64 v[140:141], v15
	v_add_u32_e32 v15, s101, v15
	s_waitcnt lgkmcnt(14)
	v_mul_f32_e32 v184, v77, v183
	v_mul_f32_e32 v185, v77, v182
	v_fma_f32 v0, v76, v182, -v184
	v_fma_f32 v1, v76, v183, v185
	v_add_f32_e32 v182, v0, v142
	v_add_f32_e32 v183, v1, v143
	ds_write_b64 v16, v[182:183]
	v_add_u32_e32 v16, s101, v16
	ds_read_b64 v[142:143], v15
	v_add_u32_e32 v15, s101, v15
	s_waitcnt lgkmcnt(14)
	v_mul_f32_e32 v184, v77, v183
	v_mul_f32_e32 v185, v77, v182
	v_fma_f32 v0, v76, v182, -v184
	v_fma_f32 v1, v76, v183, v185
	v_add_f32_e32 v182, v0, v144
	v_add_f32_e32 v183, v1, v145
	ds_write_b64 v16, v[182:183]
	v_add_u32_e32 v16, s101, v16
	ds_read_b64 v[144:145], v15
	v_add_u32_e32 v15, s101, v15
	s_waitcnt lgkmcnt(14)
	v_mul_f32_e32 v184, v77, v183
	v_mul_f32_e32 v185, v77, v182
	v_fma_f32 v0, v76, v182, -v184
	v_fma_f32 v1, v76, v183, v185
	v_add_f32_e32 v182, v0, v146
	v_add_f32_e32 v183, v1, v147
	ds_write_b64 v16, v[182:183]
	v_add_u32_e32 v16, s101, v16
	ds_read_b64 v[146:147], v15
	v_add_u32_e32 v15, s101, v15
	s_waitcnt lgkmcnt(14)
	v_mul_f32_e32 v184, v77, v183
	v_mul_f32_e32 v185, v77, v182
	v_fma_f32 v0, v76, v182, -v184
	v_fma_f32 v1, v76, v183, v185
	v_add_f32_e32 v182, v0, v132
	v_add_f32_e32 v183, v1, v133
	ds_write_b64 v16, v[182:183]
	v_add_u32_e32 v16, s101, v16
	s_waitcnt lgkmcnt(13)
	v_mul_f32_e32 v184, v77, v183
	v_mul_f32_e32 v185, v77, v182
	v_fma_f32 v0, v76, v182, -v184
	v_fma_f32 v1, v76, v183, v185
	v_add_f32_e32 v182, v0, v134
	v_add_f32_e32 v183, v1, v135
	ds_write_b64 v16, v[182:183]
	v_add_u32_e32 v16, s101, v16
	s_waitcnt lgkmcnt(12)
	v_mul_f32_e32 v184, v77, v183
	v_mul_f32_e32 v185, v77, v182
	v_fma_f32 v0, v76, v182, -v184
	v_fma_f32 v1, v76, v183, v185
	v_add_f32_e32 v182, v0, v136
	v_add_f32_e32 v183, v1, v137
	ds_write_b64 v16, v[182:183]
	v_add_u32_e32 v16, s101, v16
	s_waitcnt lgkmcnt(11)
	v_mul_f32_e32 v184, v77, v183
	v_mul_f32_e32 v185, v77, v182
	v_fma_f32 v0, v76, v182, -v184
	v_fma_f32 v1, v76, v183, v185
	v_add_f32_e32 v182, v0, v138
	v_add_f32_e32 v183, v1, v139
	ds_write_b64 v16, v[182:183]
	v_add_u32_e32 v16, s101, v16
	s_waitcnt lgkmcnt(10)
	v_mul_f32_e32 v184, v77, v183
	v_mul_f32_e32 v185, v77, v182
	v_fma_f32 v0, v76, v182, -v184
	v_fma_f32 v1, v76, v183, v185
	v_add_f32_e32 v182, v0, v140
	v_add_f32_e32 v183, v1, v141
	ds_write_b64 v16, v[182:183]
	v_add_u32_e32 v16, s101, v16
	s_waitcnt lgkmcnt(9)
	v_mul_f32_e32 v184, v77, v183
	v_mul_f32_e32 v185, v77, v182
	v_fma_f32 v0, v76, v182, -v184
	v_fma_f32 v1, v76, v183, v185
	v_add_f32_e32 v182, v0, v142
	v_add_f32_e32 v183, v1, v143
	ds_write_b64 v16, v[182:183]
	v_add_u32_e32 v16, s101, v16
	s_waitcnt lgkmcnt(8)
	v_mul_f32_e32 v184, v77, v183
	v_mul_f32_e32 v185, v77, v182
	v_fma_f32 v0, v76, v182, -v184
	v_fma_f32 v1, v76, v183, v185
	v_add_f32_e32 v182, v0, v144
	v_add_f32_e32 v183, v1, v145
	ds_write_b64 v16, v[182:183]
	v_add_u32_e32 v16, s101, v16
	s_waitcnt lgkmcnt(7)
	v_mul_f32_e32 v184, v77, v183
	v_mul_f32_e32 v185, v77, v182
	v_fma_f32 v0, v76, v182, -v184
	v_fma_f32 v1, v76, v183, v185
	v_add_f32_e32 v182, v0, v146
	v_add_f32_e32 v183, v1, v147
	ds_write_b64 v16, v[182:183]
	v_add_u32_e32 v16, s101, v16
	s_cmp_lg_u32 s55, 0
	s_cbranch_scc1 .Ls5o_nofinal
	s_sub_u32 s100, s39, 1
	s_cmp_eq_u32 s56, 0
	s_cselect_b32 s100, s100, 0
	s_cmp_lg_u32 s38, s100
	s_cbranch_scc1 .Ls5o_nofinal
	v_readlane_b32 s48, v237, 7
	v_readlane_b32 s49, v237, 8
	s_lshl_b32 s100, s47, 1
	s_add_u32 s100, s100, s36
	s_lshl_b32 s100, s100, 1
	s_add_u32 s100, s100, s56
	s_lshl_b32 s100, s100, 4
	s_add_u32 s100, s100, s99
	s_lshl_b32 s100, s100, 8
	v_lshl_add_u32 v184, v3, 2, s100
	v_add_u32_e32 v185, 0x2840000, v184
	v_add_u32_e32 v184, 0x2800000, v184
	global_store_dword v184, v182, s[48:49]
	global_store_dword v185, v183, s[48:49]
.Ls5o_nofinal:
	s_waitcnt lgkmcnt(0)
	ds_read_b128 v[132:135], v13 offset:0
	ds_read_b128 v[136:139], v13 offset:16
	ds_read_b128 v[140:143], v13 offset:128
	ds_read_b128 v[144:147], v13 offset:144
	ds_read_b128 v[148:151], v13 offset:256
	ds_read_b128 v[152:155], v13 offset:272
	ds_read_b128 v[156:159], v13 offset:384
	ds_read_b128 v[160:163], v13 offset:400
	s_waitcnt lgkmcnt(6)
	v_cvt_pk_bf16_f32 v186, v132, v133
	v_cvt_pk_bf16_f32 v187, v134, v135
	v_cvt_pk_bf16_f32 v188, v136, v137
	v_cvt_pk_bf16_f32 v189, v138, v139
	s_nop 1
	v_mfma_f32_16x16x32_bf16 v[174:177], v[186:189], v[116:119], v[174:177]
	s_waitcnt lgkmcnt(4)
	v_cvt_pk_bf16_f32 v186, v140, v141
	v_cvt_pk_bf16_f32 v187, v142, v143
	v_cvt_pk_bf16_f32 v188, v144, v145
	v_cvt_pk_bf16_f32 v189, v146, v147
	s_nop 1
	v_mfma_f32_16x16x32_bf16 v[174:177], v[186:189], v[120:123], v[174:177]
	s_waitcnt lgkmcnt(2)
	v_cvt_pk_bf16_f32 v186, v148, v149
	v_cvt_pk_bf16_f32 v187, v150, v151
	v_cvt_pk_bf16_f32 v188, v152, v153
	v_cvt_pk_bf16_f32 v189, v154, v155
	s_nop 1
	v_mfma_f32_16x16x32_bf16 v[174:177], v[186:189], v[124:127], v[174:177]
	s_waitcnt lgkmcnt(0)
	v_cvt_pk_bf16_f32 v186, v156, v157
	v_cvt_pk_bf16_f32 v187, v158, v159
	v_cvt_pk_bf16_f32 v188, v160, v161
	v_cvt_pk_bf16_f32 v189, v162, v163
	s_nop 1
	v_mfma_f32_16x16x32_bf16 v[174:177], v[186:189], v[128:131], v[174:177]
	ds_read_b128 v[132:135], v13 offset:8448
	ds_read_b128 v[136:139], v13 offset:8464
	ds_read_b128 v[140:143], v13 offset:8576
	ds_read_b128 v[144:147], v13 offset:8592
	ds_read_b128 v[148:151], v13 offset:8704
	ds_read_b128 v[152:155], v13 offset:8720
	ds_read_b128 v[156:159], v13 offset:8832
	ds_read_b128 v[160:163], v13 offset:8848
	s_waitcnt lgkmcnt(6)
	v_cvt_pk_bf16_f32 v186, v132, v133
	v_cvt_pk_bf16_f32 v187, v134, v135
	v_cvt_pk_bf16_f32 v188, v136, v137
	v_cvt_pk_bf16_f32 v189, v138, v139
	s_nop 1
	v_mfma_f32_16x16x32_bf16 v[178:181], v[186:189], v[116:119], v[178:181]
	s_waitcnt lgkmcnt(4)
	v_cvt_pk_bf16_f32 v186, v140, v141
	v_cvt_pk_bf16_f32 v187, v142, v143
	v_cvt_pk_bf16_f32 v188, v144, v145
	v_cvt_pk_bf16_f32 v189, v146, v147
	s_nop 1
	v_mfma_f32_16x16x32_bf16 v[178:181], v[186:189], v[120:123], v[178:181]
	s_waitcnt lgkmcnt(2)
	v_cvt_pk_bf16_f32 v186, v148, v149
	v_cvt_pk_bf16_f32 v187, v150, v151
	v_cvt_pk_bf16_f32 v188, v152, v153
	v_cvt_pk_bf16_f32 v189, v154, v155
	s_nop 1
	v_mfma_f32_16x16x32_bf16 v[178:181], v[186:189], v[124:127], v[178:181]
	s_waitcnt lgkmcnt(0)
	v_cvt_pk_bf16_f32 v186, v156, v157
	v_cvt_pk_bf16_f32 v187, v158, v159
	v_cvt_pk_bf16_f32 v188, v160, v161
	v_cvt_pk_bf16_f32 v189, v162, v163
	s_nop 1
	v_mfma_f32_16x16x32_bf16 v[178:181], v[186:189], v[128:131], v[178:181]
	s_add_u32 s56, s56, 1
	s_cmp_lt_u32 s56, 2
	s_cbranch_scc1 .Ls5o_dir
	s_mul_i32 s100, s46, 0x200
	s_lshl_b32 s101, s99, 5
	s_add_u32 s100, s100, s101
	s_add_u32 s100, s100, 0xcea4000
	s_add_u32 s48, s96, s100
	s_addc_u32 s49, s97, 0
	s_lshl_b32 s101, s92, 2
	v_mul_lo_u32 v18, v5, s101
	v_lshl_add_u32 v18, v4, 1, v18
	s_nop 4
	v_fmac_f32_e32 v174, v164, v165
	v_mul_f32_e32 v132, 0x3d372713, v174
	v_mul_f32_e32 v132, v174, v132
	v_fma_f32 v132, v174, v132, v174
	v_mul_f32_e32 v132, 0x3f4c422a, v132
	v_add_f32_e32 v132, v132, v132
	v_mul_f32_e32 v132, 0x3fb8aa3b, v132
	v_exp_f32_e32 v132, v132
	v_mul_f32_e32 v133, 0.5, v174
	v_add_f32_e32 v132, 1.0, v132
	v_div_scale_f32 v134, s[100:101], v132, v132, 2.0
	v_rcp_f32_e32 v135, v134
	s_nop 0
	v_fma_f32 v136, -v134, v135, 1.0
	v_fmac_f32_e32 v135, v136, v135
	v_div_scale_f32 v136, vcc, 2.0, v132, 2.0
	v_mul_f32_e32 v137, v136, v135
	v_fma_f32 v138, -v134, v137, v136
	v_fmac_f32_e32 v137, v138, v135
	v_fma_f32 v134, -v134, v137, v136
	v_div_fmas_f32 v134, v134, v135, v137
	v_div_fixup_f32 v132, v134, v132, 2.0
	v_sub_f32_e32 v132, 1.0, v132
	v_add_f32_e32 v132, 1.0, v132
	v_mul_f32_e32 v132, v133, v132
	v_bfe_u32 v133, v132, 16, 1
	v_add3_u32 v132, v132, v133, s27
	v_mov_b32_e32 v184, v18
	global_store_short_d16_hi v184, v132, s[48:49]
	s_nop 0
	v_fmac_f32_e32 v175, v164, v166
	v_mul_f32_e32 v132, 0x3d372713, v175
	v_mul_f32_e32 v132, v175, v132
	v_fma_f32 v132, v175, v132, v175
	v_mul_f32_e32 v132, 0x3f4c422a, v132
	v_add_f32_e32 v132, v132, v132
	v_mul_f32_e32 v132, 0x3fb8aa3b, v132
	v_exp_f32_e32 v132, v132
	v_mul_f32_e32 v133, 0.5, v175
	v_add_f32_e32 v132, 1.0, v132
	v_div_scale_f32 v134, s[100:101], v132, v132, 2.0
	v_rcp_f32_e32 v135, v134
	s_nop 0
	v_fma_f32 v136, -v134, v135, 1.0
	v_fmac_f32_e32 v135, v136, v135
	v_div_scale_f32 v136, vcc, 2.0, v132, 2.0
	v_mul_f32_e32 v137, v136, v135
	v_fma_f32 v138, -v134, v137, v136
	v_fmac_f32_e32 v137, v138, v135
	v_fma_f32 v134, -v134, v137, v136
	v_div_fmas_f32 v134, v134, v135, v137
	v_div_fixup_f32 v132, v134, v132, 2.0
	v_sub_f32_e32 v132, 1.0, v132
	v_add_f32_e32 v132, 1.0, v132
	v_mul_f32_e32 v132, v133, v132
	v_bfe_u32 v133, v132, 16, 1
	v_add3_u32 v132, v132, v133, s27
	v_add_u32_e32 v184, s92, v184
	global_store_short_d16_hi v184, v132, s[48:49]
	s_nop 0
	v_fmac_f32_e32 v176, v164, v167
	v_mul_f32_e32 v132, 0x3d372713, v176
	v_mul_f32_e32 v132, v176, v132
	v_fma_f32 v132, v176, v132, v176
	v_mul_f32_e32 v132, 0x3f4c422a, v132
	v_add_f32_e32 v132, v132, v132
	v_mul_f32_e32 v132, 0x3fb8aa3b, v132
	v_exp_f32_e32 v132, v132
	v_mul_f32_e32 v133, 0.5, v176
	v_add_f32_e32 v132, 1.0, v132
	v_div_scale_f32 v134, s[100:101], v132, v132, 2.0
	v_rcp_f32_e32 v135, v134
	s_nop 0
	v_fma_f32 v136, -v134, v135, 1.0
	v_fmac_f32_e32 v135, v136, v135
	v_div_scale_f32 v136, vcc, 2.0, v132, 2.0
	v_mul_f32_e32 v137, v136, v135
	v_fma_f32 v138, -v134, v137, v136
	v_fmac_f32_e32 v137, v138, v135
	v_fma_f32 v134, -v134, v137, v136
	v_div_fmas_f32 v134, v134, v135, v137
	v_div_fixup_f32 v132, v134, v132, 2.0
	v_sub_f32_e32 v132, 1.0, v132
	v_add_f32_e32 v132, 1.0, v132
	v_mul_f32_e32 v132, v133, v132
	v_bfe_u32 v133, v132, 16, 1
	v_add3_u32 v132, v132, v133, s27
	v_add_u32_e32 v184, s92, v184
	global_store_short_d16_hi v184, v132, s[48:49]
	s_nop 0
	v_fmac_f32_e32 v177, v164, v168
	v_mul_f32_e32 v132, 0x3d372713, v177
	v_mul_f32_e32 v132, v177, v132
	v_fma_f32 v132, v177, v132, v177
	v_mul_f32_e32 v132, 0x3f4c422a, v132
	v_add_f32_e32 v132, v132, v132
	v_mul_f32_e32 v132, 0x3fb8aa3b, v132
	v_exp_f32_e32 v132, v132
	v_mul_f32_e32 v133, 0.5, v177
	v_add_f32_e32 v132, 1.0, v132
	v_div_scale_f32 v134, s[100:101], v132, v132, 2.0
	v_rcp_f32_e32 v135, v134
	s_nop 0
	v_fma_f32 v136, -v134, v135, 1.0
	v_fmac_f32_e32 v135, v136, v135
	v_div_scale_f32 v136, vcc, 2.0, v132, 2.0
	v_mul_f32_e32 v137, v136, v135
	v_fma_f32 v138, -v134, v137, v136
	v_fmac_f32_e32 v137, v138, v135
	v_fma_f32 v134, -v134, v137, v136
	v_div_fmas_f32 v134, v134, v135, v137
	v_div_fixup_f32 v132, v134, v132, 2.0
	v_sub_f32_e32 v132, 1.0, v132
	v_add_f32_e32 v132, 1.0, v132
	v_mul_f32_e32 v132, v133, v132
	v_bfe_u32 v133, v132, 16, 1
	v_add3_u32 v132, v132, v133, s27
	v_add_u32_e32 v184, s92, v184
	global_store_short_d16_hi v184, v132, s[48:49]
	s_nop 0
	v_fmac_f32_e32 v178, v164, v169
	v_mul_f32_e32 v132, 0x3d372713, v178
	v_mul_f32_e32 v132, v178, v132
	v_fma_f32 v132, v178, v132, v178
	v_mul_f32_e32 v132, 0x3f4c422a, v132
	v_add_f32_e32 v132, v132, v132
	v_mul_f32_e32 v132, 0x3fb8aa3b, v132
	v_exp_f32_e32 v132, v132
	v_mul_f32_e32 v133, 0.5, v178
	v_add_f32_e32 v132, 1.0, v132
	v_div_scale_f32 v134, s[100:101], v132, v132, 2.0
	v_rcp_f32_e32 v135, v134
	s_nop 0
	v_fma_f32 v136, -v134, v135, 1.0
	v_fmac_f32_e32 v135, v136, v135
	v_div_scale_f32 v136, vcc, 2.0, v132, 2.0
	v_mul_f32_e32 v137, v136, v135
	v_fma_f32 v138, -v134, v137, v136
	v_fmac_f32_e32 v137, v138, v135
	v_fma_f32 v134, -v134, v137, v136
	v_div_fmas_f32 v134, v134, v135, v137
	v_div_fixup_f32 v132, v134, v132, 2.0
	v_sub_f32_e32 v132, 1.0, v132
	v_add_f32_e32 v132, 1.0, v132
	v_mul_f32_e32 v132, v133, v132
	v_bfe_u32 v133, v132, 16, 1
	v_add3_u32 v132, v132, v133, s27
	v_add_u32_e32 v184, s8, v18
	global_store_short_d16_hi v184, v132, s[48:49]
	s_nop 0
	v_fmac_f32_e32 v179, v164, v170
	v_mul_f32_e32 v132, 0x3d372713, v179
	v_mul_f32_e32 v132, v179, v132
	v_fma_f32 v132, v179, v132, v179
	v_mul_f32_e32 v132, 0x3f4c422a, v132
	v_add_f32_e32 v132, v132, v132
	v_mul_f32_e32 v132, 0x3fb8aa3b, v132
	v_exp_f32_e32 v132, v132
	v_mul_f32_e32 v133, 0.5, v179
	v_add_f32_e32 v132, 1.0, v132
	v_div_scale_f32 v134, s[100:101], v132, v132, 2.0
	v_rcp_f32_e32 v135, v134
	s_nop 0
	v_fma_f32 v136, -v134, v135, 1.0
	v_fmac_f32_e32 v135, v136, v135
	v_div_scale_f32 v136, vcc, 2.0, v132, 2.0
	v_mul_f32_e32 v137, v136, v135
	v_fma_f32 v138, -v134, v137, v136
	v_fmac_f32_e32 v137, v138, v135
	v_fma_f32 v134, -v134, v137, v136
	v_div_fmas_f32 v134, v134, v135, v137
	v_div_fixup_f32 v132, v134, v132, 2.0
	v_sub_f32_e32 v132, 1.0, v132
	v_add_f32_e32 v132, 1.0, v132
	v_mul_f32_e32 v132, v133, v132
	v_bfe_u32 v133, v132, 16, 1
	v_add3_u32 v132, v132, v133, s27
	v_add_u32_e32 v184, s92, v184
	global_store_short_d16_hi v184, v132, s[48:49]
	s_nop 0
	v_fmac_f32_e32 v180, v164, v171
	v_mul_f32_e32 v132, 0x3d372713, v180
	v_mul_f32_e32 v132, v180, v132
	v_fma_f32 v132, v180, v132, v180
	v_mul_f32_e32 v132, 0x3f4c422a, v132
	v_add_f32_e32 v132, v132, v132
	v_mul_f32_e32 v132, 0x3fb8aa3b, v132
	v_exp_f32_e32 v132, v132
	v_mul_f32_e32 v133, 0.5, v180
	v_add_f32_e32 v132, 1.0, v132
	v_div_scale_f32 v134, s[100:101], v132, v132, 2.0
	v_rcp_f32_e32 v135, v134
	s_nop 0
	v_fma_f32 v136, -v134, v135, 1.0
	v_fmac_f32_e32 v135, v136, v135
	v_div_scale_f32 v136, vcc, 2.0, v132, 2.0
	v_mul_f32_e32 v137, v136, v135
	v_fma_f32 v138, -v134, v137, v136
	v_fmac_f32_e32 v137, v138, v135
	v_fma_f32 v134, -v134, v137, v136
	v_div_fmas_f32 v134, v134, v135, v137
	v_div_fixup_f32 v132, v134, v132, 2.0
	v_sub_f32_e32 v132, 1.0, v132
	v_add_f32_e32 v132, 1.0, v132
	v_mul_f32_e32 v132, v133, v132
	v_bfe_u32 v133, v132, 16, 1
	v_add3_u32 v132, v132, v133, s27
	v_add_u32_e32 v184, s92, v184
	global_store_short_d16_hi v184, v132, s[48:49]
	s_nop 0
	v_fmac_f32_e32 v181, v164, v172
	v_mul_f32_e32 v132, 0x3d372713, v181
	v_mul_f32_e32 v132, v181, v132
	v_fma_f32 v132, v181, v132, v181
	v_mul_f32_e32 v132, 0x3f4c422a, v132
	v_add_f32_e32 v132, v132, v132
	v_mul_f32_e32 v132, 0x3fb8aa3b, v132
	v_exp_f32_e32 v132, v132
	v_mul_f32_e32 v133, 0.5, v181
	v_add_f32_e32 v132, 1.0, v132
	v_div_scale_f32 v134, s[100:101], v132, v132, 2.0
	v_rcp_f32_e32 v135, v134
	s_nop 0
	v_fma_f32 v136, -v134, v135, 1.0
	v_fmac_f32_e32 v135, v136, v135
	v_div_scale_f32 v136, vcc, 2.0, v132, 2.0
	v_mul_f32_e32 v137, v136, v135
	v_fma_f32 v138, -v134, v137, v136
	v_fmac_f32_e32 v137, v138, v135
	v_fma_f32 v134, -v134, v137, v136
	v_div_fmas_f32 v134, v134, v135, v137
	v_div_fixup_f32 v132, v134, v132, 2.0
	v_sub_f32_e32 v132, 1.0, v132
	v_add_f32_e32 v132, 1.0, v132
	v_mul_f32_e32 v132, v133, v132
	v_bfe_u32 v133, v132, 16, 1
	v_add3_u32 v132, v132, v133, s27
	v_add_u32_e32 v184, s92, v184
	global_store_short_d16_hi v184, v132, s[48:49]
	s_nop 0
	s_sub_u32 s43, s43, 1
	s_cmp_eq_u32 s43, 0
	s_cbranch_scc1 .Ls5o_done
	s_lshl_b32 s100, s63, 2
	s_add_u32 s100, s100, s40
	s_add_u32 s100, s100, 0x800
	s_branch .Ls5o_task
.Ls5o_done:
	s_waitcnt lgkmcnt(0)
	s_branch .LBB0_618
